# both WG classes end P2 in the dynamic LRU-summary queue (int8 tiles first); LRU1_N 1920
# speedup vs baseline: 1.0210x; 1.0079x over previous
.LBB0_175:
	s_cmp_lg_u32 s32, 1
	s_cbranch_scc1 .Lp0_done_mode0
	s_waitcnt vmcnt(0) lgkmcnt(0)
	s_barrier
	s_mov_b32 s32, 0
	s_add_i32 s2, s97, 0x70
	s_lshl_b32 s2, s2, 11
	v_lshl_add_u32 v209, v0, 2, s2
	s_add_u32 s2, s76, 0x30c00000
	s_addc_u32 s3, s77, 0
	global_load_dword v210, v209, s[2:3]
	s_add_u32 s2, s2, 0x80000
	s_addc_u32 s3, s3, 0
	global_load_dword v211, v209, s[2:3]
	s_add_u32 s2, s2, 0x80000
	s_addc_u32 s3, s3, 0
	global_load_dword v0, v209, s[2:3]
	s_add_u32 s2, s2, 0x80000
	s_addc_u32 s3, s3, 0
	global_load_dword v1, v209, s[2:3]
	s_add_u32 s2, s2, 0x80000
	s_addc_u32 s3, s3, 0
	global_load_dword v5, v209, s[2:3]
	s_add_u32 s2, s2, 0x80000
	s_addc_u32 s3, s3, 0
	global_load_dword v6, v209, s[2:3]
	s_add_u32 s2, s2, 0x80000
	s_addc_u32 s3, s3, 0
	global_load_dword v8, v209, s[2:3]
	s_add_u32 s2, s2, 0x80000
	s_addc_u32 s3, s3, 0
	global_load_dword v36, v209, s[2:3]
	s_add_u32 s2, s2, 0x80000
	s_addc_u32 s3, s3, 0
	global_load_dword v37, v209, s[2:3]
	s_add_u32 s2, s2, 0x80000
	s_addc_u32 s3, s3, 0
	global_load_dword v38, v209, s[2:3]
	s_add_u32 s2, s2, 0x80000
	s_addc_u32 s3, s3, 0
	global_load_dword v39, v209, s[2:3]
	s_add_u32 s2, s2, 0x80000
	s_addc_u32 s3, s3, 0
	global_load_dword v40, v209, s[2:3]
	s_add_u32 s2, s2, 0x80000
	s_addc_u32 s3, s3, 0
	global_load_dword v41, v209, s[2:3]
	s_add_u32 s2, s2, 0x80000
	s_addc_u32 s3, s3, 0
	global_load_dword v42, v209, s[2:3]
	s_add_u32 s2, s2, 0x80000
	s_addc_u32 s3, s3, 0
	global_load_dword v43, v209, s[2:3]
	s_add_u32 s2, s2, 0x80000
	s_addc_u32 s3, s3, 0
	global_load_dword v44, v209, s[2:3]
	s_add_u32 s2, s2, 0x80000
	s_addc_u32 s3, s3, 0
	global_load_dword v45, v209, s[2:3]
	s_add_u32 s2, s2, 0x80000
	s_addc_u32 s3, s3, 0
	global_load_dword v50, v209, s[2:3]
	s_add_u32 s2, s2, 0x80000
	s_addc_u32 s3, s3, 0
	global_load_dword v51, v209, s[2:3]
	s_add_u32 s2, s2, 0x80000
	s_addc_u32 s3, s3, 0
	global_load_dword v52, v209, s[2:3]
	s_add_u32 s2, s2, 0x80000
	s_addc_u32 s3, s3, 0
	global_load_dword v53, v209, s[2:3]
	s_add_u32 s2, s2, 0x80000
	s_addc_u32 s3, s3, 0
	global_load_dword v54, v209, s[2:3]
	s_add_u32 s2, s2, 0x80000
	s_addc_u32 s3, s3, 0
	global_load_dword v55, v209, s[2:3]
	s_add_u32 s2, s2, 0x80000
	s_addc_u32 s3, s3, 0
	global_load_dword v56, v209, s[2:3]
	s_add_u32 s2, s2, 0x80000
	s_addc_u32 s3, s3, 0
	global_load_dword v57, v209, s[2:3]
	s_add_u32 s2, s2, 0x80000
	s_addc_u32 s3, s3, 0
	global_load_dword v62, v209, s[2:3]
	s_add_u32 s2, s2, 0x80000
	s_addc_u32 s3, s3, 0
	global_load_dword v63, v209, s[2:3]
	s_add_u32 s2, s2, 0x80000
	s_addc_u32 s3, s3, 0
	global_load_dword v64, v209, s[2:3]
	s_add_u32 s2, s2, 0x80000
	s_addc_u32 s3, s3, 0
	global_load_dword v65, v209, s[2:3]
	s_add_u32 s2, s2, 0x80000
	s_addc_u32 s3, s3, 0
	global_load_dword v70, v209, s[2:3]
	s_add_u32 s2, s2, 0x80000
	s_addc_u32 s3, s3, 0
	global_load_dword v71, v209, s[2:3]
	s_add_u32 s2, s2, 0x80000
	s_addc_u32 s3, s3, 0
	global_load_dword v72, v209, s[2:3]
	s_add_u32 s2, s2, 0x80000
	s_addc_u32 s3, s3, 0
	global_load_dword v73, v209, s[2:3]
	s_add_u32 s2, s2, 0x80000
	s_addc_u32 s3, s3, 0
	global_load_dword v82, v209, s[2:3]
	s_add_u32 s2, s2, 0x80000
	s_addc_u32 s3, s3, 0
	global_load_dword v83, v209, s[2:3]
	s_add_u32 s2, s2, 0x80000
	s_addc_u32 s3, s3, 0
	global_load_dword v84, v209, s[2:3]
	s_add_u32 s2, s2, 0x80000
	s_addc_u32 s3, s3, 0
	global_load_dword v85, v209, s[2:3]
	s_add_u32 s2, s2, 0x80000
	s_addc_u32 s3, s3, 0
	global_load_dword v88, v209, s[2:3]
	s_add_u32 s2, s2, 0x80000
	s_addc_u32 s3, s3, 0
	global_load_dword v89, v209, s[2:3]
	s_add_u32 s2, s2, 0x80000
	s_addc_u32 s3, s3, 0
	global_load_dword v94, v209, s[2:3]
	s_add_u32 s2, s2, 0x80000
	s_addc_u32 s3, s3, 0
	global_load_dword v95, v209, s[2:3]
	s_add_u32 s2, s2, 0x80000
	s_addc_u32 s3, s3, 0
	global_load_dword v96, v209, s[2:3]
	s_add_u32 s2, s2, 0x80000
	s_addc_u32 s3, s3, 0
	global_load_dword v97, v209, s[2:3]
	s_add_u32 s2, s2, 0x80000
	s_addc_u32 s3, s3, 0
	global_load_dword v102, v209, s[2:3]
	s_add_u32 s2, s2, 0x80000
	s_addc_u32 s3, s3, 0
	global_load_dword v103, v209, s[2:3]
	s_add_u32 s2, s2, 0x80000
	s_addc_u32 s3, s3, 0
	global_load_dword v104, v209, s[2:3]
	s_add_u32 s2, s2, 0x80000
	s_addc_u32 s3, s3, 0
	global_load_dword v105, v209, s[2:3]
	s_add_u32 s2, s2, 0x80000
	s_addc_u32 s3, s3, 0
	global_load_dword v122, v209, s[2:3]
	s_add_u32 s2, s2, 0x80000
	s_addc_u32 s3, s3, 0
	global_load_dword v123, v209, s[2:3]
	s_add_u32 s2, s2, 0x80000
	s_addc_u32 s3, s3, 0
	global_load_dword v124, v209, s[2:3]
	s_add_u32 s2, s2, 0x80000
	s_addc_u32 s3, s3, 0
	global_load_dword v125, v209, s[2:3]
	s_add_u32 s2, s2, 0x80000
	s_addc_u32 s3, s3, 0
	global_load_dword v170, v209, s[2:3]
	s_add_u32 s2, s2, 0x80000
	s_addc_u32 s3, s3, 0
	global_load_dword v171, v209, s[2:3]
	s_add_u32 s2, s2, 0x80000
	s_addc_u32 s3, s3, 0
	global_load_dword v172, v209, s[2:3]
	s_add_u32 s2, s2, 0x80000
	s_addc_u32 s3, s3, 0
	global_load_dword v173, v209, s[2:3]
	s_add_u32 s2, s2, 0x80000
	s_addc_u32 s3, s3, 0
	global_load_dword v174, v209, s[2:3]
	s_add_u32 s2, s2, 0x80000
	s_addc_u32 s3, s3, 0
	global_load_dword v175, v209, s[2:3]
	s_add_u32 s2, s2, 0x80000
	s_addc_u32 s3, s3, 0
	global_load_dword v195, v209, s[2:3]
	s_add_u32 s2, s2, 0x80000
	s_addc_u32 s3, s3, 0
	global_load_dword v197, v209, s[2:3]
	s_add_u32 s2, s2, 0x80000
	s_addc_u32 s3, s3, 0
	global_load_dword v254, v209, s[2:3]
	s_add_u32 s2, s2, 0x80000
	s_addc_u32 s3, s3, 0
	global_load_dword v255, v209, s[2:3]
	s_waitcnt vmcnt(0)
	v_readlane_b32 s64, v211, 0
	v_readlane_b32 s65, v211, 1
	v_readlane_b32 s66, v211, 2
	v_readlane_b32 s67, v211, 3
	v_readlane_b32 s68, v211, 4
	v_readlane_b32 s69, v211, 5
	v_readlane_b32 s70, v211, 6
	v_readlane_b32 s71, v211, 7
	v_readlane_b32 s72, v211, 8
	v_readlane_b32 s73, v211, 9
	v_readlane_b32 s74, v211, 10
	v_readlane_b32 s75, v211, 11
	v_readlane_b32 s76, v211, 12
	v_readlane_b32 s77, v211, 13
	v_readlane_b32 s78, v211, 14
	v_readlane_b32 s79, v211, 15
	v_readlane_b32 s80, v211, 16
	v_readlane_b32 s81, v211, 17
	v_readlane_b32 s82, v211, 18
	v_readlane_b32 s83, v211, 19
	v_readlane_b32 s84, v211, 20
	v_readlane_b32 s85, v211, 21
	v_readlane_b32 s86, v211, 22
	v_readlane_b32 s87, v211, 23
	v_readlane_b32 s88, v211, 24
	v_readlane_b32 s89, v211, 25
	v_readlane_b32 s90, v211, 26
	v_readlane_b32 s91, v211, 27
	v_readlane_b32 s92, v211, 28
	v_readlane_b32 s93, v211, 29
	v_readlane_b32 s94, v211, 30
	v_readlane_b32 s95, v211, 31
	v_readlane_b32 s96, v211, 32
	v_readlane_b32 s97, v211, 33
	v_readlane_b32 s0, v210, 0
	v_readlane_b32 s1, v210, 1
	v_readlane_b32 s2, v210, 2
	v_readlane_b32 s3, v210, 3
	v_readlane_b32 s4, v210, 4
	v_readlane_b32 s5, v210, 5
	v_readlane_b32 s6, v210, 6
	v_readlane_b32 s7, v210, 7
	v_readlane_b32 s8, v210, 8
	v_readlane_b32 s9, v210, 9
	v_readlane_b32 s10, v210, 10
	v_readlane_b32 s11, v210, 11
	v_readlane_b32 s12, v210, 12
	v_readlane_b32 s13, v210, 13
	v_readlane_b32 s14, v210, 14
	v_readlane_b32 s15, v210, 15
	v_readlane_b32 s16, v210, 16
	v_readlane_b32 s17, v210, 17
	v_readlane_b32 s18, v210, 18
	v_readlane_b32 s19, v210, 19
	v_readlane_b32 s20, v210, 20
	v_readlane_b32 s21, v210, 21
	v_readlane_b32 s22, v210, 22
	v_readlane_b32 s23, v210, 23
	v_readlane_b32 s24, v210, 24
	v_readlane_b32 s25, v210, 25
	v_readlane_b32 s26, v210, 26
	v_readlane_b32 s27, v210, 27
	v_readlane_b32 s28, v210, 28
	v_readlane_b32 s29, v210, 29
	v_readlane_b32 s30, v210, 30
	v_readlane_b32 s31, v210, 31
	v_readlane_b32 s33, v210, 33
	v_readlane_b32 s34, v210, 34
	v_readlane_b32 s35, v210, 35
	v_readlane_b32 s36, v210, 36
	v_readlane_b32 s37, v210, 37
	v_readlane_b32 s38, v210, 38
	v_readlane_b32 s39, v210, 39
	v_readlane_b32 s40, v210, 40
	v_readlane_b32 s41, v210, 41
	v_readlane_b32 s42, v210, 42
	v_readlane_b32 s43, v210, 43
	v_readlane_b32 s44, v210, 44
	v_readlane_b32 s45, v210, 45
	v_readlane_b32 s46, v210, 46
	v_readlane_b32 s47, v210, 47
	v_readlane_b32 s48, v210, 48
	v_readlane_b32 s49, v210, 49
	v_readlane_b32 s50, v210, 50
	v_readlane_b32 s51, v210, 51
	v_readlane_b32 s52, v210, 52
	v_readlane_b32 s53, v210, 53
	v_readlane_b32 s54, v210, 54
	v_readlane_b32 s55, v210, 55
	v_readlane_b32 s56, v210, 56
	v_readlane_b32 s57, v210, 57
	v_readlane_b32 s58, v210, 58
	v_readlane_b32 s59, v210, 59
	v_readlane_b32 s60, v210, 60
	v_readlane_b32 s61, v210, 61
	v_readlane_b32 s62, v210, 62
	v_readlane_b32 s63, v210, 63
	s_mov_b32 s32, 2
	s_nop 4
	s_branch .LBB0_361

.LBB0_361:
	s_cmp_lg_u32 s32, 0
	s_cbranch_scc1 .Lsnap_done
	s_cmpk_lt_i32 s97, 0x70
	s_cbranch_scc0 .Lsnap_done
	v_writelane_b32 v2, s0, 0
	v_writelane_b32 v2, s1, 1
	v_writelane_b32 v2, s2, 2
	v_writelane_b32 v2, s3, 3
	v_writelane_b32 v2, s4, 4
	v_writelane_b32 v2, s5, 5
	v_writelane_b32 v2, s6, 6
	v_writelane_b32 v2, s7, 7
	v_writelane_b32 v2, s8, 8
	v_writelane_b32 v2, s9, 9
	v_writelane_b32 v2, s10, 10
	v_writelane_b32 v2, s11, 11
	v_writelane_b32 v2, s12, 12
	v_writelane_b32 v2, s13, 13
	v_writelane_b32 v2, s14, 14
	v_writelane_b32 v2, s15, 15
	v_writelane_b32 v2, s16, 16
	v_writelane_b32 v2, s17, 17
	v_writelane_b32 v2, s18, 18
	v_writelane_b32 v2, s19, 19
	v_writelane_b32 v2, s20, 20
	v_writelane_b32 v2, s21, 21
	v_writelane_b32 v2, s22, 22
	v_writelane_b32 v2, s23, 23
	v_writelane_b32 v2, s24, 24
	v_writelane_b32 v2, s25, 25
	v_writelane_b32 v2, s26, 26
	v_writelane_b32 v2, s27, 27
	v_writelane_b32 v2, s28, 28
	v_writelane_b32 v2, s29, 29
	v_writelane_b32 v2, s30, 30
	v_writelane_b32 v2, s31, 31
	v_writelane_b32 v2, s32, 32
	v_writelane_b32 v2, s33, 33
	v_writelane_b32 v2, s34, 34
	v_writelane_b32 v2, s35, 35
	v_writelane_b32 v2, s36, 36
	v_writelane_b32 v2, s37, 37
	v_writelane_b32 v2, s38, 38
	v_writelane_b32 v2, s39, 39
	v_writelane_b32 v2, s40, 40
	v_writelane_b32 v2, s41, 41
	v_writelane_b32 v2, s42, 42
	v_writelane_b32 v2, s43, 43
	v_writelane_b32 v2, s44, 44
	v_writelane_b32 v2, s45, 45
	v_writelane_b32 v2, s46, 46
	v_writelane_b32 v2, s47, 47
	v_writelane_b32 v2, s48, 48
	v_writelane_b32 v2, s49, 49
	v_writelane_b32 v2, s50, 50
	v_writelane_b32 v2, s51, 51
	v_writelane_b32 v2, s52, 52
	v_writelane_b32 v2, s53, 53
	v_writelane_b32 v2, s54, 54
	v_writelane_b32 v2, s55, 55
	v_writelane_b32 v2, s56, 56
	v_writelane_b32 v2, s57, 57
	v_writelane_b32 v2, s58, 58
	v_writelane_b32 v2, s59, 59
	v_writelane_b32 v2, s60, 60
	v_writelane_b32 v2, s61, 61
	v_writelane_b32 v2, s62, 62
	v_writelane_b32 v2, s63, 63
	v_writelane_b32 v3, s64, 0
	v_writelane_b32 v3, s65, 1
	v_writelane_b32 v3, s66, 2
	v_writelane_b32 v3, s67, 3
	v_writelane_b32 v3, s68, 4
	v_writelane_b32 v3, s69, 5
	v_writelane_b32 v3, s70, 6
	v_writelane_b32 v3, s71, 7
	v_writelane_b32 v3, s72, 8
	v_writelane_b32 v3, s73, 9
	v_writelane_b32 v3, s74, 10
	v_writelane_b32 v3, s75, 11
	v_writelane_b32 v3, s76, 12
	v_writelane_b32 v3, s77, 13
	v_writelane_b32 v3, s78, 14
	v_writelane_b32 v3, s79, 15
	v_writelane_b32 v3, s80, 16
	v_writelane_b32 v3, s81, 17
	v_writelane_b32 v3, s82, 18
	v_writelane_b32 v3, s83, 19
	v_writelane_b32 v3, s84, 20
	v_writelane_b32 v3, s85, 21
	v_writelane_b32 v3, s86, 22
	v_writelane_b32 v3, s87, 23
	v_writelane_b32 v3, s88, 24
	v_writelane_b32 v3, s89, 25
	v_writelane_b32 v3, s90, 26
	v_writelane_b32 v3, s91, 27
	v_writelane_b32 v3, s92, 28
	v_writelane_b32 v3, s93, 29
	v_writelane_b32 v3, s94, 30
	v_writelane_b32 v3, s95, 31
	v_writelane_b32 v3, s96, 32
	v_writelane_b32 v3, s97, 33
	s_lshl_b32 s2, s97, 11
	v_lshl_add_u32 v4, v0, 2, s2
	s_add_u32 s2, s76, 0x30c00000
	s_addc_u32 s3, s77, 0
	global_store_dword v4, v2, s[2:3]
	s_add_u32 s2, s2, 0x80000
	s_addc_u32 s3, s3, 0
	global_store_dword v4, v3, s[2:3]
	s_add_u32 s2, s2, 0x80000
	s_addc_u32 s3, s3, 0
	s_add_u32 s2, s2, 0x80000
	s_addc_u32 s3, s3, 0
	s_add_u32 s2, s2, 0x80000
	s_addc_u32 s3, s3, 0
	s_add_u32 s2, s2, 0x80000
	s_addc_u32 s3, s3, 0
	s_add_u32 s2, s2, 0x80000
	s_addc_u32 s3, s3, 0
	s_add_u32 s2, s2, 0x80000
	s_addc_u32 s3, s3, 0
	s_add_u32 s2, s2, 0x80000
	s_addc_u32 s3, s3, 0
	s_add_u32 s2, s2, 0x80000
	s_addc_u32 s3, s3, 0
	s_add_u32 s2, s2, 0x80000
	s_addc_u32 s3, s3, 0
	s_add_u32 s2, s2, 0x80000
	s_addc_u32 s3, s3, 0
	s_add_u32 s2, s2, 0x80000
	s_addc_u32 s3, s3, 0
	s_add_u32 s2, s2, 0x80000
	s_addc_u32 s3, s3, 0
	s_add_u32 s2, s2, 0x80000
	s_addc_u32 s3, s3, 0
	s_add_u32 s2, s2, 0x80000
	s_addc_u32 s3, s3, 0
	s_add_u32 s2, s2, 0x80000
	s_addc_u32 s3, s3, 0
	s_add_u32 s2, s2, 0x80000
	s_addc_u32 s3, s3, 0
	s_add_u32 s2, s2, 0x80000
	s_addc_u32 s3, s3, 0
	s_add_u32 s2, s2, 0x80000
	s_addc_u32 s3, s3, 0
	s_add_u32 s2, s2, 0x80000
	s_addc_u32 s3, s3, 0
	s_add_u32 s2, s2, 0x80000
	s_addc_u32 s3, s3, 0
	s_add_u32 s2, s2, 0x80000
	s_addc_u32 s3, s3, 0
	s_add_u32 s2, s2, 0x80000
	s_addc_u32 s3, s3, 0
	s_add_u32 s2, s2, 0x80000
	s_addc_u32 s3, s3, 0
	s_add_u32 s2, s2, 0x80000
	s_addc_u32 s3, s3, 0
	s_add_u32 s2, s2, 0x80000
	s_addc_u32 s3, s3, 0
	s_add_u32 s2, s2, 0x80000
	s_addc_u32 s3, s3, 0
	s_add_u32 s2, s2, 0x80000
	s_addc_u32 s3, s3, 0
	s_add_u32 s2, s2, 0x80000
	s_addc_u32 s3, s3, 0
	s_add_u32 s2, s2, 0x80000
	s_addc_u32 s3, s3, 0
	s_add_u32 s2, s2, 0x80000
	s_addc_u32 s3, s3, 0
	s_add_u32 s2, s2, 0x80000
	s_addc_u32 s3, s3, 0
	s_add_u32 s2, s2, 0x80000
	s_addc_u32 s3, s3, 0
	s_add_u32 s2, s2, 0x80000
	s_addc_u32 s3, s3, 0
	s_add_u32 s2, s2, 0x80000
	s_addc_u32 s3, s3, 0
	s_add_u32 s2, s2, 0x80000
	s_addc_u32 s3, s3, 0
	s_add_u32 s2, s2, 0x80000
	s_addc_u32 s3, s3, 0
	s_add_u32 s2, s2, 0x80000
	s_addc_u32 s3, s3, 0
	s_add_u32 s2, s2, 0x80000
	s_addc_u32 s3, s3, 0
	s_add_u32 s2, s2, 0x80000
	s_addc_u32 s3, s3, 0
	s_add_u32 s2, s2, 0x80000
	s_addc_u32 s3, s3, 0
	s_add_u32 s2, s2, 0x80000
	s_addc_u32 s3, s3, 0
	s_add_u32 s2, s2, 0x80000
	s_addc_u32 s3, s3, 0
	s_add_u32 s2, s2, 0x80000
	s_addc_u32 s3, s3, 0
	s_add_u32 s2, s2, 0x80000
	s_addc_u32 s3, s3, 0
	s_add_u32 s2, s2, 0x80000
	s_addc_u32 s3, s3, 0
	s_add_u32 s2, s2, 0x80000
	s_addc_u32 s3, s3, 0
	s_add_u32 s2, s2, 0x80000
	s_addc_u32 s3, s3, 0
	s_add_u32 s2, s2, 0x80000
	s_addc_u32 s3, s3, 0
	s_add_u32 s2, s2, 0x80000
	s_addc_u32 s3, s3, 0
	s_add_u32 s2, s2, 0x80000
	s_addc_u32 s3, s3, 0
	s_add_u32 s2, s2, 0x80000
	s_addc_u32 s3, s3, 0
	s_add_u32 s2, s2, 0x80000
	s_addc_u32 s3, s3, 0
	s_add_u32 s2, s2, 0x80000
	s_addc_u32 s3, s3, 0
	s_add_u32 s2, s2, 0x80000
	s_addc_u32 s3, s3, 0
	global_store_dword v4, v174, s[2:3]
	s_add_u32 s2, s2, 0x80000
	s_addc_u32 s3, s3, 0
	global_store_dword v4, v175, s[2:3]
	s_add_u32 s2, s2, 0x80000
	s_addc_u32 s3, s3, 0
	global_store_dword v4, v195, s[2:3]
	s_add_u32 s2, s2, 0x80000
	s_addc_u32 s3, s3, 0
	global_store_dword v4, v197, s[2:3]
	s_add_u32 s2, s2, 0x80000
	s_addc_u32 s3, s3, 0
	s_add_u32 s2, s2, 0x80000
	s_addc_u32 s3, s3, 0
	s_waitcnt vmcnt(0)
	v_readlane_b32 s2, v2, 2
	v_readlane_b32 s3, v2, 3
	s_mov_b32 s32, 2

.LBB0_657:
	s_mov_b64 s[14:15], exec
	v_readlane_b32 s16, v254, 17
	v_readlane_b32 s17, v254, 18
	s_and_b64 s[16:17], s[14:15], s[16:17]
	s_mov_b64 exec, s[16:17]
	v_mov_b32_e32 v2, s42
	ds_write_b32 v2, v161
	s_or_b64 exec, exec, s[14:15]
	s_waitcnt lgkmcnt(0)
	s_barrier
	ds_read_b32 v2, v169
	s_movk_i32 s14, 0x77f
	s_waitcnt lgkmcnt(0)
	v_cmp_lt_i32_e64 s[14:15], s14, v2
	v_readfirstlane_b32 s34, v2
	s_and_b64 vcc, exec, s[14:15]
	s_cbranch_vccnz .LBB0_656
	s_mov_b64 s[16:17], exec
	v_readlane_b32 s18, v254, 17
	v_readlane_b32 s19, v254, 18
	s_and_b64 s[18:19], s[16:17], s[18:19]
	s_mov_b64 exec, s[18:19]
	s_cbranch_execz .LBB0_664
	s_mov_b64 s[20:21], exec
	v_mbcnt_lo_u32_b32 v2, s20, 0
	v_mbcnt_hi_u32_b32 v2, s21, v2
	v_cmp_eq_u32_e32 vcc, 0, v2
	s_and_saveexec_b64 s[18:19], vcc
	s_cbranch_execz .LBB0_663
	s_bcnt1_i32_b64 s20, s[20:21]
	v_mov_b32_e32 v3, s20
	global_atomic_add v3, v147, v3, s[76:77] offset:512 sc0

.LBB0_1015:
	s_cmp_eq_u32 s32, 2
	s_cbranch_scc0 .Lr_cont
	s_mov_b32 s32, 3
	s_lshl_b32 s2, s97, 11
	v_lshl_add_u32 v4, v0, 2, s2
	s_add_u32 s2, s76, 0x30c00000
	s_addc_u32 s3, s77, 0
	global_load_dword v2, v4, s[2:3]
	s_add_u32 s2, s2, 0x80000
	s_addc_u32 s3, s3, 0
	global_load_dword v3, v4, s[2:3]
	s_add_u32 s2, s2, 0x80000
	s_addc_u32 s3, s3, 0
	s_add_u32 s2, s2, 0x80000
	s_addc_u32 s3, s3, 0
	s_add_u32 s2, s2, 0x80000
	s_addc_u32 s3, s3, 0
	s_add_u32 s2, s2, 0x80000
	s_addc_u32 s3, s3, 0
	s_add_u32 s2, s2, 0x80000
	s_addc_u32 s3, s3, 0
	s_add_u32 s2, s2, 0x80000
	s_addc_u32 s3, s3, 0
	s_add_u32 s2, s2, 0x80000
	s_addc_u32 s3, s3, 0
	s_add_u32 s2, s2, 0x80000
	s_addc_u32 s3, s3, 0
	s_add_u32 s2, s2, 0x80000
	s_addc_u32 s3, s3, 0
	s_add_u32 s2, s2, 0x80000
	s_addc_u32 s3, s3, 0
	s_add_u32 s2, s2, 0x80000
	s_addc_u32 s3, s3, 0
	s_add_u32 s2, s2, 0x80000
	s_addc_u32 s3, s3, 0
	s_add_u32 s2, s2, 0x80000
	s_addc_u32 s3, s3, 0
	s_add_u32 s2, s2, 0x80000
	s_addc_u32 s3, s3, 0
	s_add_u32 s2, s2, 0x80000
	s_addc_u32 s3, s3, 0
	s_add_u32 s2, s2, 0x80000
	s_addc_u32 s3, s3, 0
	s_add_u32 s2, s2, 0x80000
	s_addc_u32 s3, s3, 0
	s_add_u32 s2, s2, 0x80000
	s_addc_u32 s3, s3, 0
	s_add_u32 s2, s2, 0x80000
	s_addc_u32 s3, s3, 0
	s_add_u32 s2, s2, 0x80000
	s_addc_u32 s3, s3, 0
	s_add_u32 s2, s2, 0x80000
	s_addc_u32 s3, s3, 0
	s_add_u32 s2, s2, 0x80000
	s_addc_u32 s3, s3, 0
	s_add_u32 s2, s2, 0x80000
	s_addc_u32 s3, s3, 0
	s_add_u32 s2, s2, 0x80000
	s_addc_u32 s3, s3, 0
	s_add_u32 s2, s2, 0x80000
	s_addc_u32 s3, s3, 0
	s_add_u32 s2, s2, 0x80000
	s_addc_u32 s3, s3, 0
	s_add_u32 s2, s2, 0x80000
	s_addc_u32 s3, s3, 0
	s_add_u32 s2, s2, 0x80000
	s_addc_u32 s3, s3, 0
	s_add_u32 s2, s2, 0x80000
	s_addc_u32 s3, s3, 0
	s_add_u32 s2, s2, 0x80000
	s_addc_u32 s3, s3, 0
	s_add_u32 s2, s2, 0x80000
	s_addc_u32 s3, s3, 0
	s_add_u32 s2, s2, 0x80000
	s_addc_u32 s3, s3, 0
	s_add_u32 s2, s2, 0x80000
	s_addc_u32 s3, s3, 0
	s_add_u32 s2, s2, 0x80000
	s_addc_u32 s3, s3, 0
	s_add_u32 s2, s2, 0x80000
	s_addc_u32 s3, s3, 0
	s_add_u32 s2, s2, 0x80000
	s_addc_u32 s3, s3, 0
	s_add_u32 s2, s2, 0x80000
	s_addc_u32 s3, s3, 0
	s_add_u32 s2, s2, 0x80000
	s_addc_u32 s3, s3, 0
	s_add_u32 s2, s2, 0x80000
	s_addc_u32 s3, s3, 0
	s_add_u32 s2, s2, 0x80000
	s_addc_u32 s3, s3, 0
	s_add_u32 s2, s2, 0x80000
	s_addc_u32 s3, s3, 0
	s_add_u32 s2, s2, 0x80000
	s_addc_u32 s3, s3, 0
	s_add_u32 s2, s2, 0x80000
	s_addc_u32 s3, s3, 0
	s_add_u32 s2, s2, 0x80000
	s_addc_u32 s3, s3, 0
	s_add_u32 s2, s2, 0x80000
	s_addc_u32 s3, s3, 0
	s_add_u32 s2, s2, 0x80000
	s_addc_u32 s3, s3, 0
	s_add_u32 s2, s2, 0x80000
	s_addc_u32 s3, s3, 0
	s_add_u32 s2, s2, 0x80000
	s_addc_u32 s3, s3, 0
	s_add_u32 s2, s2, 0x80000
	s_addc_u32 s3, s3, 0
	s_add_u32 s2, s2, 0x80000
	s_addc_u32 s3, s3, 0
	s_add_u32 s2, s2, 0x80000
	s_addc_u32 s3, s3, 0
	s_add_u32 s2, s2, 0x80000
	s_addc_u32 s3, s3, 0
	s_add_u32 s2, s2, 0x80000
	s_addc_u32 s3, s3, 0
	s_add_u32 s2, s2, 0x80000
	s_addc_u32 s3, s3, 0
	global_load_dword v174, v4, s[2:3]
	s_add_u32 s2, s2, 0x80000
	s_addc_u32 s3, s3, 0
	global_load_dword v175, v4, s[2:3]
	s_add_u32 s2, s2, 0x80000
	s_addc_u32 s3, s3, 0
	global_load_dword v195, v4, s[2:3]
	s_add_u32 s2, s2, 0x80000
	s_addc_u32 s3, s3, 0
	global_load_dword v197, v4, s[2:3]
	s_add_u32 s2, s2, 0x80000
	s_addc_u32 s3, s3, 0
	s_add_u32 s2, s2, 0x80000
	s_addc_u32 s3, s3, 0
	s_waitcnt vmcnt(0)
	v_readlane_b32 s0, v2, 0
	v_readlane_b32 s1, v2, 1
	v_readlane_b32 s4, v2, 4
	v_readlane_b32 s5, v2, 5
	v_readlane_b32 s6, v2, 6
	v_readlane_b32 s14, v2, 14
	v_readlane_b32 s20, v2, 20
	v_readlane_b32 s27, v2, 27
	v_readlane_b32 s34, v2, 34
	v_readlane_b32 s61, v2, 61
	v_readlane_b32 s70, v3, 6
	v_readlane_b32 s71, v3, 7
	v_readlane_b32 s89, v3, 25
	s_mov_b64 s[0:1], 0
	s_nop 4
	s_branch .LBB0_361

.LBB0_1069:
	v_readlane_b32 s52, v254, 10
	s_cmp_lt_i32 s52, 4
	s_cselect_b64 s[2:3], -1, 0
	s_and_b64 s[20:21], s[2:3], s[0:1]
	v_readlane_b32 s53, v254, 11
	v_readlane_b32 s54, v254, 12
	s_andn2_b64 vcc, exec, s[20:21]
	v_readlane_b32 s55, v254, 13
	s_cbranch_vccnz .LBB0_1396
	s_bitcmp0_b32 s54, 0
	s_cselect_b64 s[0:1], -1, 0
	s_cmpk_gt_i32 s97, 127
	s_cselect_b64 s[2:3], -1, 0
	s_or_b64 s[0:1], s[0:1], s[2:3]
	s_mov_b32 s61, 0
	s_and_b64 vcc, exec, s[0:1]
	s_cbranch_vccnz .LBB0_1147
	s_add_i32 s0, s97, 0x780
	v_and_b32_e32 v146, 48, v1
	v_mov_b32_e32 v147, 0
	s_add_u32 s24, s76, 0x26200000
	v_lshl_add_u64 v[2:3], s[76:77], 0, v[146:147]
	s_mov_b64 s[2:3], 0x500000
	s_addc_u32 s25, s77, 0
	s_movk_i32 s1, 0x200
	v_lshl_add_u64 v[148:149], v[2:3], 0, s[2:3]
	v_lshrrev_b32_e32 v2, 3, v0
	v_lshlrev_b32_e32 v3, 4, v0
	v_cmp_gt_u32_e64 s[8:9], s1, v0
	s_movk_i32 s1, 0x210
	s_add_u32 s37, s76, 0x300000
	v_and_b32_e32 v161, 0x70, v3
	v_mad_u32_u24 v3, v2, s1, 0
	s_addc_u32 s44, s77, 0
	s_ashr_i32 s1, s0, 31
	s_lshl_b64 s[14:15], s[60:61], 12
	s_lshl_b64 s[16:17], s[0:1], 15
	v_add_u32_e32 v162, -3, v2
	v_add_u32_e32 v163, -2, v2
	v_add_u32_e32 v164, -1, v2
	v_cndmask_b32_e64 v165, 0, v2, s[8:9]
	v_lshlrev_b32_e32 v2, 8, v2
	s_add_u32 s1, s16, s14
	v_sub_u32_e32 v2, v3, v2
	s_addc_u32 s15, s17, s15
	v_lshl_add_u32 v167, v161, 1, v2
	v_or_b32_e32 v2, 48, v1
	s_add_u32 s14, s76, s1
	v_add_u32_e32 v6, 0, v146
	v_mul_u32_u24_e32 v7, 0x110, v2
	v_and_b32_e32 v2, 16, v0
	v_lshlrev_b32_e32 v146, 4, v1
	s_addc_u32 s15, s77, s15
	v_and_b32_e32 v4, 15, v0
	v_lshl_add_u32 v166, v161, 2, v3
	v_cmp_eq_u32_e64 s[10:11], 0, v2
	v_lshl_add_u64 v[2:3], s[14:15], 0, v[146:147]
	s_mov_b64 s[14:15], 0x44b00800
	v_lshrrev_b32_e32 v5, 4, v1
	v_lshl_or_b32 v160, s60, 4, v4
	v_lshl_add_u64 v[154:155], v[2:3], 0, s[14:15]
	v_cndmask_b32_e64 v150, 0, 1.0, s[8:9]
	v_mul_u32_u24_e32 v4, 0x110, v4
	v_lshl_add_u32 v8, v160, 2, 0
	v_mul_u32_u24_e32 v5, 0x840, v5
	s_ashr_i32 s97, s96, 31
	s_mov_b32 s38, 0x3e2aaaab
	v_mbcnt_lo_u32_b32 v2, -1, 0
	v_cmp_lt_u32_e64 s[2:3], 23, v0
	v_cmp_lt_u32_e64 s[4:5], 15, v0
	v_cmp_lt_u32_e64 s[6:7], 7, v0
	v_mov_b32_e32 v151, v150
	v_mov_b32_e32 v152, v150
	v_mov_b32_e32 v153, v150
	v_cmp_gt_u32_e64 s[12:13], 16, v1
	s_lshl_b64 s[26:27], s[96:97], 15
	v_readlane_b32 s97, v254, 60
	s_mov_b64 s[28:29], 0x2000
	s_movk_i32 s1, 0x2000
	s_mov_b64 s[30:31], 0x4000
	s_movk_i32 s45, 0x4000
	s_mov_b64 s[34:35], 0x6000
	v_add_u32_e32 v168, v6, v4
	v_add_u32_e32 v169, v6, v7
	s_mov_b32 s46, 0x3f2aaaab
	v_mov_b32_e32 v170, 0x3ecc95a3
	s_mov_b32 s47, 0x3f317218
	s_mov_b32 s48, 0x7f800000
	s_mov_b32 s49, 0x33800000
	s_mov_b32 s50, 0xbe800000
	s_mov_b32 s39, 0x3e124925
	v_mov_b32_e32 v156, 0x3f317218
	v_mov_b32_e32 v171, 0x7f800000
	v_mov_b32_e32 v172, 0x7fc00000
	v_mov_b32_e32 v173, 0xff800000
	v_add_u32_e32 v174, v8, v5
	v_mbcnt_hi_u32_b32 v175, -1, v2
	s_branch .LBB0_1073
